# P0 rope tables: f64 Taylor recurrence multiplies by exact-rounded reciprocal constants instead of 26 IEEE f64 divisions per entry
# speedup vs baseline: 1.0004x; 1.0004x over previous
; DI void sincos_acc(float angf, float& sn, float& cs) {
;     const double x = (double)angf;
;     const double n = rint(x * 0.15915494309189535);
;     double r = fma(-n, 6.283185307179586, x); r = fma(-n, 2.4492935982947064e-16, r);
;     const double r2 = r * r;
;     double ts = r, ss = r, tc = 1.0, cc = 1.0;
;     for (int k = 1; k <= 13; ++k) {
;         ts *= -r2 / (double)((2 * k) * (2 * k + 1)); ss += ts;
;         tc *= -r2 / (double)((2 * k - 1) * (2 * k)); cc += tc;
;     }
;     sn = (float)ss; cs = (float)cc;
; }
.LBB0_122:
	v_ashrrev_i32_e32 v5, 5, v6
	v_cvt_f32_i32_e32 v5, v5
	v_mul_f32_e32 v5, v3, v5
	v_cvt_f64_f32_e32 v[18:19], v5
	v_mul_f64 v[8:9], v[18:19], s[8:9]
	v_rndne_f64_e32 v[8:9], v[8:9]
	v_fmac_f64_e32 v[18:19], s[22:23], v[8:9]
	v_fmac_f64_e32 v[18:19], s[26:27], v[8:9]
	v_mul_f64 v[8:9], v[18:19], -v[18:19]
	v_mov_b64_e32 v[12:13], 1.0
	v_mov_b64_e32 v[10:11], v[18:19]
	v_mov_b64_e32 v[14:15], v[18:19]
	v_mov_b64_e32 v[20:21], 1.0
	s_mov_b32 s28, 0x55555555
	s_mov_b32 s29, 0x3fc55555
	s_mov_b32 s30, 0x00000000
	s_mov_b32 s31, 0x3fe00000
	v_mul_f64 v[22:23], v[8:9], s[28:29]
	v_mul_f64 v[24:25], v[8:9], s[30:31]
	v_fmac_f64_e32 v[14:15], v[10:11], v[22:23]
	v_fmac_f64_e32 v[20:21], v[12:13], v[24:25]
	v_mul_f64 v[10:11], v[10:11], v[22:23]
	v_mul_f64 v[12:13], v[12:13], v[24:25]
	s_mov_b32 s28, 0x9999999a
	s_mov_b32 s29, 0x3fa99999
	s_mov_b32 s30, 0x55555555
	s_mov_b32 s31, 0x3fb55555
	v_mul_f64 v[22:23], v[8:9], s[28:29]
	v_mul_f64 v[24:25], v[8:9], s[30:31]
	v_fmac_f64_e32 v[14:15], v[10:11], v[22:23]
	v_fmac_f64_e32 v[20:21], v[12:13], v[24:25]
	v_mul_f64 v[10:11], v[10:11], v[22:23]
	v_mul_f64 v[12:13], v[12:13], v[24:25]
	s_mov_b32 s28, 0x18618618
	s_mov_b32 s29, 0x3f986186
	s_mov_b32 s30, 0x11111111
	s_mov_b32 s31, 0x3fa11111
	v_mul_f64 v[22:23], v[8:9], s[28:29]
	v_mul_f64 v[24:25], v[8:9], s[30:31]
	v_fmac_f64_e32 v[14:15], v[10:11], v[22:23]
	v_fmac_f64_e32 v[20:21], v[12:13], v[24:25]
	v_mul_f64 v[10:11], v[10:11], v[22:23]
	v_mul_f64 v[12:13], v[12:13], v[24:25]
	s_mov_b32 s28, 0x1c71c71c
	s_mov_b32 s29, 0x3f8c71c7
	s_mov_b32 s30, 0x92492492
	s_mov_b32 s31, 0x3f924924
	v_mul_f64 v[22:23], v[8:9], s[28:29]
	v_mul_f64 v[24:25], v[8:9], s[30:31]
	v_fmac_f64_e32 v[14:15], v[10:11], v[22:23]
	v_fmac_f64_e32 v[20:21], v[12:13], v[24:25]
	v_mul_f64 v[10:11], v[10:11], v[22:23]
	v_mul_f64 v[12:13], v[12:13], v[24:25]
	s_mov_b32 s28, 0x29e4129e
	s_mov_b32 s29, 0x3f829e41
	s_mov_b32 s30, 0x16c16c17
	s_mov_b32 s31, 0x3f86c16c
	v_mul_f64 v[22:23], v[8:9], s[28:29]
	v_mul_f64 v[24:25], v[8:9], s[30:31]
	v_fmac_f64_e32 v[14:15], v[10:11], v[22:23]
	v_fmac_f64_e32 v[20:21], v[12:13], v[24:25]
	v_mul_f64 v[10:11], v[10:11], v[22:23]
	v_mul_f64 v[12:13], v[12:13], v[24:25]
	s_mov_b32 s28, 0x1a41a41a
	s_mov_b32 s29, 0x3f7a41a4
	s_mov_b32 s30, 0xf07c1f08
	s_mov_b32 s31, 0x3f7f07c1
	v_mul_f64 v[22:23], v[8:9], s[28:29]
	v_mul_f64 v[24:25], v[8:9], s[30:31]
	v_fmac_f64_e32 v[14:15], v[10:11], v[22:23]
	v_fmac_f64_e32 v[20:21], v[12:13], v[24:25]
	v_mul_f64 v[10:11], v[10:11], v[22:23]
	v_mul_f64 v[12:13], v[12:13], v[24:25]
	s_mov_b32 s28, 0x13813814
	s_mov_b32 s29, 0x3f738138
	s_mov_b32 s30, 0x16816817
	s_mov_b32 s31, 0x3f768168
	v_mul_f64 v[22:23], v[8:9], s[28:29]
	v_mul_f64 v[24:25], v[8:9], s[30:31]
	v_fmac_f64_e32 v[14:15], v[10:11], v[22:23]
	v_fmac_f64_e32 v[20:21], v[12:13], v[24:25]
	v_mul_f64 v[10:11], v[10:11], v[22:23]
	v_mul_f64 v[12:13], v[12:13], v[24:25]
	s_mov_b32 s28, 0x1e1e1e1e
	s_mov_b32 s29, 0x3f6e1e1e
	s_mov_b32 s30, 0x11111111
	s_mov_b32 s31, 0x3f711111
	v_mul_f64 v[22:23], v[8:9], s[28:29]
	v_mul_f64 v[24:25], v[8:9], s[30:31]
	v_fmac_f64_e32 v[14:15], v[10:11], v[22:23]
	v_fmac_f64_e32 v[20:21], v[12:13], v[24:25]
	v_mul_f64 v[10:11], v[10:11], v[22:23]
	v_mul_f64 v[12:13], v[12:13], v[24:25]
	s_mov_b32 s28, 0xfd017f40
	s_mov_b32 s29, 0x3f67f405
	s_mov_b32 s30, 0x1ac5701b
	s_mov_b32 s31, 0x3f6ac570
	v_mul_f64 v[22:23], v[8:9], s[28:29]
	v_mul_f64 v[24:25], v[8:9], s[30:31]
	v_fmac_f64_e32 v[14:15], v[10:11], v[22:23]
	v_fmac_f64_e32 v[20:21], v[12:13], v[24:25]
	v_mul_f64 v[10:11], v[10:11], v[22:23]
	v_mul_f64 v[12:13], v[12:13], v[24:25]
	s_mov_b32 s28, 0x13813814
	s_mov_b32 s29, 0x3f638138
	s_mov_b32 s30, 0x308158ed
	s_mov_b32 s31, 0x3f658ed2
	v_mul_f64 v[22:23], v[8:9], s[28:29]
	v_mul_f64 v[24:25], v[8:9], s[30:31]
	v_fmac_f64_e32 v[14:15], v[10:11], v[22:23]
	v_fmac_f64_e32 v[20:21], v[12:13], v[24:25]
	v_mul_f64 v[10:11], v[10:11], v[22:23]
	v_mul_f64 v[12:13], v[12:13], v[24:25]
	s_mov_b32 s28, 0xb51f5e1a
	s_mov_b32 s29, 0x3f603091
	s_mov_b32 s30, 0x4046ed29
	s_mov_b32 s31, 0x3f61bb4a
	v_mul_f64 v[22:23], v[8:9], s[28:29]
	v_mul_f64 v[24:25], v[8:9], s[30:31]
	v_fmac_f64_e32 v[14:15], v[10:11], v[22:23]
	v_fmac_f64_e32 v[20:21], v[12:13], v[24:25]
	v_mul_f64 v[10:11], v[10:11], v[22:23]
	v_mul_f64 v[12:13], v[12:13], v[24:25]
	s_mov_b32 s28, 0xb4e81b4f
	s_mov_b32 s29, 0x3f5b4e81
	s_mov_b32 s30, 0x76b981db
	s_mov_b32 s31, 0x3f5dae60
	v_mul_f64 v[22:23], v[8:9], s[28:29]
	v_mul_f64 v[24:25], v[8:9], s[30:31]
	v_fmac_f64_e32 v[14:15], v[10:11], v[22:23]
	v_fmac_f64_e32 v[20:21], v[12:13], v[24:25]
	v_mul_f64 v[10:11], v[10:11], v[22:23]
	v_mul_f64 v[12:13], v[12:13], v[24:25]
	s_mov_b32 s28, 0xc201756d
	s_mov_b32 s29, 0x3f5756ca
	s_mov_b32 s30, 0x7f9b2ce6
	s_mov_b32 s31, 0x3f5934c6
	v_mul_f64 v[22:23], v[8:9], s[28:29]
	v_mul_f64 v[24:25], v[8:9], s[30:31]
	v_fmac_f64_e32 v[14:15], v[10:11], v[22:23]
	v_fmac_f64_e32 v[20:21], v[12:13], v[24:25]
	s_branch .LBB0_121
